# dilated X pass takes its Q fragments from the Y-pass registers through the idle K/V staging LDS instead of re-loading them from global
# speedup vs baseline: 1.0303x; 1.0073x over previous
; DI void qt_init(QT& t, const bf16_t* qrow, int h) {
;     const bf16x8* qp = (const bf16x8*)qrow;
; #pragma unroll
;     for (int ks = 0; ks < 4; ++ks) t.qf[ks] = qp[2 * ks + h];
; DI void attn_a_x(unsigned char* ws, LAS unsigned char* buf, int bh, int ra, int i0, int lane) {
;     ...
;     const int qpa = ra + 16 * (i0 + r), qpb = qpa + 8;
;     const float m0 = ((const float*)(ws + WS_GAINS))[400];
;     QT a, b; qt_init(a, Q + (size_t)qpa * 64, h); qt_init(b, Q + (size_t)qpb * 64, h);
.LBB0_601:
	ds_bpermute_b32 v64, v191, v189
	ds_bpermute_b32 v65, v191, v188
	v_and_b32_e32 v66, 7, v234
	v_lshlrev_b32_e32 v66, 5, v66
	v_lshrrev_b32_e32 v67, 6, v234
	v_lshl_add_u32 v66, v67, 2, v66
	v_bfe_u32 v80, v234, 4, 1
	v_add_u32_e32 v66, v66, v80
	v_mul_u32_u24_e32 v66, 0x110, v66
	v_bfe_u32 v80, v234, 5, 1
	v_lshlrev_b32_e32 v80, 4, v80
	v_add_u32_e32 v66, v66, v80
	v_add_u32_e32 v66, 0x12000, v66
	v_lshlrev_b32_e32 v67, 5, v67
	v_and_b32_e32 v68, 31, v234
	v_add_u32_e32 v67, v67, v68
	v_mul_u32_u24_e32 v67, 0x110, v67
	v_add_u32_e32 v67, v67, v80
	v_add_u32_e32 v67, 0x12000, v67
	v_and_b32_e32 v68, 7, v234
	v_lshl_add_u32 v66, v68, 4, v66
	v_lshrrev_b32_e32 v68, 6, v234
	v_lshl_add_u32 v67, v68, 4, v67
	s_waitcnt lgkmcnt(0)
	v_add_f32_e32 v64, v189, v64
	v_add_f32_e32 v65, v188, v65
	s_mov_b32 exec_lo, 0xff00ff
	s_mov_b32 exec_hi, 0xff00ff
	ds_write_b128 v66, v[32:35] offset:0
	ds_write_b128 v66, v[36:39] offset:32
	ds_write_b128 v66, v[40:43] offset:64
	ds_write_b128 v66, v[44:47] offset:96
	ds_write_b128 v66, v[48:51] offset:128
	ds_write_b128 v66, v[52:55] offset:160
	ds_write_b128 v66, v[56:59] offset:192
	ds_write_b128 v66, v[60:63] offset:224
	ds_write_b128 v66, v[16:19] offset:544
	ds_write_b128 v66, v[20:23] offset:576
	ds_write_b128 v66, v[24:27] offset:608
	ds_write_b128 v66, v[28:31] offset:640
	ds_write_b128 v66, v[0:3] offset:672
	ds_write_b128 v66, v[4:7] offset:704
	ds_write_b128 v66, v[8:11] offset:736
	ds_write_b128 v66, v[12:15] offset:768
	s_mov_b32 exec_hi, 0
	ds_write_b32 v66, v64 offset:256
	ds_write_b32 v66, v65 offset:800
	s_mov_b64 exec, -1
	s_waitcnt lgkmcnt(0)
	s_barrier
	ds_read_b128 v[144:147], v67 offset:0
	ds_read_b128 v[148:151], v67 offset:32
	ds_read_b128 v[152:155], v67 offset:64
	ds_read_b128 v[156:159], v67 offset:96
	ds_read_b128 v[160:163], v67 offset:128
	ds_read_b128 v[164:167], v67 offset:160
	ds_read_b128 v[168:171], v67 offset:192
	ds_read_b128 v[172:175], v67 offset:224
	v_mov_b32_e32 v68, 0
	s_mov_b32 exec_hi, 0
	ds_read_b32 v68, v67 offset:256
	s_mov_b64 exec, -1
	v_and_b32_e32 v77, 7, v234
	v_bfe_u32 v78, v234, 3, 1
	v_lshl_or_b32 v69, v77, 1, v78
	v_lshlrev_b32_e32 v69, 5, v69
	v_lshrrev_b32_e32 v78, 6, v234
	v_lshl_add_u32 v69, v78, 2, v69
	v_bfe_u32 v79, v234, 4, 1
	v_add_u32_e32 v69, v69, v79
	v_mul_u32_u24_e32 v69, 0x90, v69
	v_bfe_u32 v79, v234, 5, 1
	v_add_u32_e32 v77, v77, v79
	v_add_u32_e32 v72, 6, v77
	v_and_b32_e32 v72, 7, v72
	v_lshl_add_u32 v72, v72, 4, v69
	v_add_u32_e32 v71, 4, v77
	v_and_b32_e32 v71, 7, v71
	v_lshl_add_u32 v71, v71, 4, v69
	v_add_u32_e32 v70, 2, v77
	v_and_b32_e32 v70, 7, v70
	v_lshl_add_u32 v70, v70, 4, v69
	v_and_b32_e32 v77, 7, v77
	v_lshl_add_u32 v69, v77, 4, v69
	v_lshlrev_b32_e32 v73, 6, v78
	v_and_b32_e32 v77, 31, v234
	v_add_u32_e32 v73, v73, v77
	v_mul_u32_u24_e32 v73, 0x90, v73
	v_add_u32_e32 v77, v78, v79
	v_add_u32_e32 v76, 6, v77
	v_and_b32_e32 v76, 7, v76
	v_lshl_add_u32 v76, v76, 4, v73
	v_add_u32_e32 v75, 4, v77
	v_and_b32_e32 v75, 7, v75
	v_lshl_add_u32 v75, v75, 4, v73
	v_add_u32_e32 v74, 2, v77
	v_and_b32_e32 v74, 7, v74
	v_lshl_add_u32 v74, v74, 4, v73
	v_and_b32_e32 v77, 7, v77
	v_lshl_add_u32 v73, v77, 4, v73
	ds_write_b128 v69, v[112:115]
	ds_write_b128 v70, v[116:119]
	ds_write_b128 v71, v[120:123]
	ds_write_b128 v72, v[124:127]
	ds_write_b128 v69, v[128:131] offset:288
	ds_write_b128 v70, v[132:135] offset:288
	ds_write_b128 v71, v[136:139] offset:288
	ds_write_b128 v72, v[140:143] offset:288
	s_waitcnt lgkmcnt(0)
	s_barrier
	s_mov_b32 exec_lo, 0xff00ff00
	s_mov_b32 exec_hi, 0xff00ff00
	ds_write_b128 v66, v[32:35] offset:0
	ds_write_b128 v66, v[36:39] offset:32
	ds_write_b128 v66, v[40:43] offset:64
	ds_write_b128 v66, v[44:47] offset:96
	ds_write_b128 v66, v[48:51] offset:128
	ds_write_b128 v66, v[52:55] offset:160
	ds_write_b128 v66, v[56:59] offset:192
	ds_write_b128 v66, v[60:63] offset:224
	ds_write_b128 v66, v[16:19] offset:544
	ds_write_b128 v66, v[20:23] offset:576
	ds_write_b128 v66, v[24:27] offset:608
	ds_write_b128 v66, v[28:31] offset:640
	ds_write_b128 v66, v[0:3] offset:672
	ds_write_b128 v66, v[4:7] offset:704
	ds_write_b128 v66, v[8:11] offset:736
	ds_write_b128 v66, v[12:15] offset:768
	s_mov_b32 exec_hi, 0
	ds_write_b32 v66, v64 offset:256
	ds_write_b32 v66, v65 offset:800
	s_mov_b64 exec, -1
	s_waitcnt lgkmcnt(0)
	s_barrier
.LBB0_603:
	s_lshl_b32 s16, s56, 5
	v_or_b32_e32 v0, s16, v214
	v_lshlrev_b32_e32 v81, 4, v0
	v_add_u32_e32 v186, s22, v81
	v_ashrrev_i32_e32 v187, 31, v186
	v_add_u32_e32 v188, 8, v186
	v_ashrrev_i32_e32 v189, 31, v188
	s_waitcnt lgkmcnt(0)
	global_load_dword v80, v183, s[68:69]
	ds_read_b128 v[16:19], v67 offset:0
	ds_read_b128 v[20:23], v67 offset:32
	ds_read_b128 v[24:27], v67 offset:64
	ds_read_b128 v[28:31], v67 offset:96
	ds_read_b128 v[0:3], v67 offset:128
	ds_read_b128 v[4:7], v67 offset:160
	ds_read_b128 v[8:11], v67 offset:192
	ds_read_b128 v[12:15], v67 offset:224
	ds_read_b128 v[136:139], v73
	ds_read_b128 v[128:131], v74
	ds_read_b128 v[124:127], v75
	ds_read_b128 v[112:115], v76
	ds_read_b128 v[140:143], v73 offset:4608
	ds_read_b128 v[132:135], v74 offset:4608
	ds_read_b128 v[120:123], v75 offset:4608
	ds_read_b128 v[116:119], v76 offset:4608
	v_mov_b32_e32 v202, 0
	s_mov_b32 exec_hi, 0
	ds_read_b32 v202, v67 offset:256
	s_mov_b64 exec, -1
	v_mov_b32_e32 v203, v68
	v_mov_b32_e32 v48, v144
	v_mov_b32_e32 v49, v145
	v_mov_b32_e32 v50, v146
	v_mov_b32_e32 v51, v147
	v_mov_b32_e32 v52, v148
	v_mov_b32_e32 v53, v149
	v_mov_b32_e32 v54, v150
	v_mov_b32_e32 v55, v151
	v_mov_b32_e32 v56, v152
	v_mov_b32_e32 v57, v153
	v_mov_b32_e32 v58, v154
	v_mov_b32_e32 v59, v155
	v_mov_b32_e32 v60, v156
	v_mov_b32_e32 v61, v157
	v_mov_b32_e32 v62, v158
	v_mov_b32_e32 v63, v159
	v_mov_b32_e32 v32, v160
	v_mov_b32_e32 v33, v161
	v_mov_b32_e32 v34, v162
	v_mov_b32_e32 v35, v163
	v_mov_b32_e32 v36, v164
	v_mov_b32_e32 v37, v165
	v_mov_b32_e32 v38, v166
	v_mov_b32_e32 v39, v167
	v_mov_b32_e32 v40, v168
	v_mov_b32_e32 v41, v169
	v_mov_b32_e32 v42, v170
	v_mov_b32_e32 v43, v171
	v_mov_b32_e32 v44, v172
	v_mov_b32_e32 v45, v173
	v_mov_b32_e32 v46, v174
	v_mov_b32_e32 v47, v175
	s_waitcnt lgkmcnt(0)
	s_barrier
	s_cmp_gt_u32 s56, 3
	s_mov_b32 s63, 0
	s_cbranch_scc1 .LBB0_610
